# v21 + P2 short-conv loop: loads prefetched one 4-token iteration ahead AND 64-lane sums via DPP/permlane swaps (probe shows conv section 15.6 -> 6.9 us when combined)
# speedup vs baseline: 1.0044x; 1.0044x over previous
; #define GAS __attribute__((address_space(1)))
; __device__ __forceinline__ void unpack8(const v4u w, float (&f)[8]) { f[0] = bflo(w.x); f[1] = bfhi(w.x); f[2] = bflo(w.y); f[3] = bfhi(w.y); f[4] = bflo(w.z); f[5] = bfhi(w.z); f[6] = bflo(w.w); f[7] = bfhi(w.w); }
; __device__ __forceinline__ void attn_conv_unit(LAS unsigned char* lds, int unit, const bf16* Z, bf16* Y, float* RA,
;                                                const float* qg, const float* kg, const float* sinks, const float* convw) {
;     ...
;         const size_t tokw = tok0 + 16 * wave;
;         float u1[8], u2[8];
; #pragma unroll
;         for (int e = 0; e < 8; ++e) { u1[e] = 0.f; u2[e] = 0.f; }
;         if (qb > 0 || wave > 0) {
;             unpack8(*(const GAS v4u*)(Z + (tokw - 1) * ZLD + O_U + c0), u1);
;             unpack8(*(const GAS v4u*)(Z + (tokw - 2) * ZLD + O_U + c0), u2);
;         }
; #pragma unroll 4
;         for (int i = 0; i < 16; ++i) {
;             const size_t tok = tokw + i;
;             float fb[8], fu[8];
;             unpack8(__builtin_nontemporal_load((const GAS v4u*)(Z + tok * ZLD + O_B + c0)), fb); unpack8(__builtin_nontemporal_load((const GAS v4u*)(Z + tok * ZLD + O_U + c0)), fu);
;             float ov[8]; float ss = 0.f;
; #pragma unroll
;             for (int e = 0; e < 8; ++e) { const float u0 = fu[e]; const float cv = w0[e] * u2[e] + w1[e] * u1[e] + w2[e] * u0; ov[e] = fb[e] * cv; ss += ov[e] * ov[e]; u2[e] = u1[e]; u1[e] = u0; }
.LBB0_435:
	s_and_b32 s48, s93, 63
	s_lshl_b32 s47, s48, 7
	s_lshl_b32 s74, s48, 18
	s_mul_i32 vcc_lo, s48, 0x70000
	s_add_u32 s48, s56, s47
	s_addc_u32 s49, s57, 0
	s_add_u32 s48, s48, s3
	s_addc_u32 s49, s49, 0
	s_mul_i32 s3, s49, 0xe00
	s_mul_hi_u32 s60, s48, 0xe00
	s_add_i32 s3, s60, s3
	s_mul_i32 s60, s48, 0xe00
	s_add_u32 s60, s66, s60
	s_addc_u32 s61, s67, s3
	s_lshl_b64 s[48:49], s[48:49], 11
	s_add_u32 s84, s94, s48
	s_addc_u32 s85, s95, s49
	s_lshl_b64 s[48:49], s[88:89], 24
	s_or_b32 s3, s48, s74
	s_lshl_b64 s[74:75], s[78:79], 15
	s_add_u32 s3, s3, s74
	s_addc_u32 s48, s49, s75
	s_add_u32 s86, s70, s3
	s_addc_u32 s87, s71, s48
	s_mul_i32 s48, s88, 0x1c00000
	s_mul_hi_i32 s3, s88, 0x1c00000
	s_add_u32 s48, s48, vcc_lo
	s_addc_u32 s3, s3, 0
	s_mul_i32 s74, s78, 0xe000
	s_mul_hi_u32 s49, s78, 0xe000
	s_add_u32 s48, s48, s74
	s_addc_u32 s3, s3, s49
	s_waitcnt vmcnt(5)
	v_mov_b32_e32 v26, v2
	s_waitcnt vmcnt(1)
	v_mov_b32_e32 v32, v17
	s_waitcnt vmcnt(0)
	v_mov_b32_e32 v17, v21
	s_add_u32 s88, s66, s48
	v_mov_b32_e32 v27, v6
	v_mov_b32_e32 v30, v10
	v_mov_b32_e32 v31, v14
	v_swap_b32 v6, v5
	v_swap_b32 v14, v13
	v_mov_b32_e32 v2, v1
	v_swap_b32 v10, v9
	v_swap_b32 v21, v22
	v_mov_b32_e32 v1, v26
	v_mov_b32_e32 v17, v18
	v_mov_b32_e32 v18, v32
	s_addc_u32 s89, s67, s3
	s_mov_b32 s3, 16
	v_lshl_add_u64 v[252:253], s[60:61], 0, v[136:137]
	global_load_dwordx4 v[182:185], v[252:253], off offset:2560 nt
	global_load_dwordx4 v[186:189], v[252:253], off offset:1536 nt
	v_lshl_add_u64 v[254:255], s[88:89], 0, v[136:137]
	s_mov_b64 s[100:101], 0x1000
	v_lshl_add_u64 v[252:253], v[254:255], 0, s[100:101]
	global_load_dwordx4 v[190:193], v[252:253], off offset:2048 nt
	global_load_dwordx4 v[194:197], v[252:253], off offset:1024 nt
	s_mov_b64 s[100:101], 0x2000
	v_lshl_add_u64 v[252:253], v[254:255], 0, s[100:101]
	global_load_dwordx4 v[198:201], v[252:253], off offset:1536 nt
	global_load_dwordx4 v[202:205], v[252:253], off offset:512 nt
	s_mov_b64 s[100:101], 0x3000
	v_lshl_add_u64 v[252:253], v[254:255], 0, s[100:101]
	global_load_dwordx4 v[206:209], v[252:253], off offset:1024 nt
	global_load_dwordx4 v[210:213], v[252:253], off nt
	s_mov_b64 s[100:101], 0x3800
	s_waitcnt vmcnt(0)
.LBB0_436:
	v_lshl_add_u64 v[26:27], s[60:61], 0, v[136:137]
	s_waitcnt vmcnt(11)
	v_lshl_add_u64 v[252:253], v[26:27], 0, s[100:101]
	v_mov_b32_e32 v52, v182
	v_mov_b32_e32 v53, v183
	v_mov_b32_e32 v54, v184
	v_mov_b32_e32 v55, v185
	global_load_dwordx4 v[182:185], v[252:253], off offset:2560 nt
	s_waitcnt vmcnt(11)
	v_lshl_add_u64 v[252:253], v[26:27], 0, s[100:101]
	v_mov_b32_e32 v56, v186
	v_mov_b32_e32 v57, v187
	v_mov_b32_e32 v58, v188
	v_mov_b32_e32 v59, v189
	global_load_dwordx4 v[186:189], v[252:253], off offset:1536 nt
	v_pk_mul_f32 v[30:31], v[6:7], v[40:41]
	v_pk_mul_f32 v[40:41], v[10:11], v[24:25]
	v_mov_b32_e32 v44, v48
	v_mov_b32_e32 v42, v49
	v_lshl_add_u64 v[48:49], s[88:89], 0, v[136:137]
	s_movk_i32 s48, 0x1000
	v_pk_fma_f32 v[36:37], v[2:3], v[36:37], v[40:41]
	v_add_co_u32_e32 v40, vcc, s48, v48
	v_lshl_add_u64 v[46:47], s[86:87], 0, v[136:137]
	s_mov_b32 s49, 0x1a000000
	v_addc_co_u32_e32 v41, vcc, 0, v49, vcc
	v_add_co_u32_e32 v62, vcc, s49, v46
	s_movk_i32 s74, 0x2000
	s_nop 0
	v_addc_co_u32_e32 v63, vcc, 0, v47, vcc
	v_add_co_u32_e32 v64, vcc, s74, v48
	s_mov_b32 s75, 0x1a001000
	s_nop 0
	v_addc_co_u32_e32 v65, vcc, 0, v49, vcc
	v_mov_b32_e32 v34, v38
	v_add_co_u32_e32 v46, vcc, s75, v46
	v_mov_b32_e32 v32, v39
	v_pk_mul_f32 v[26:27], v[4:5], v[34:35]
	v_pk_mul_f32 v[34:35], v[8:9], v[42:43]
	v_addc_co_u32_e32 v47, vcc, 0, v47, vcc
	v_pk_mul_f32 v[50:51], v[6:7], v[28:29]
	v_pk_fma_f32 v[30:31], v[14:15], v[28:29], v[30:31]
	v_add_co_u32_e32 v28, vcc, s91, v48
	v_pk_fma_f32 v[26:27], v[12:13], v[44:45], v[26:27]
	v_pk_fma_f32 v[32:33], v[0:1], v[32:33], v[34:35]
	v_pk_mul_f32 v[60:61], v[4:5], v[44:45]
	v_addc_co_u32_e32 v29, vcc, 0, v49, vcc
	v_lshl_add_u64 v[38:39], s[84:85], 0, v[136:137]
	s_add_u32 s60, s60, 0x3800
	s_addc_u32 s61, s61, 0
	s_add_u32 s84, s84, 0x2000
	s_addc_u32 s85, s85, 0
	s_add_u32 s86, s86, 0x2000
	s_addc_u32 s87, s87, 0
	s_add_i32 s3, s3, -4
	s_add_u32 s88, s88, 0x3800
	s_addc_u32 s89, s89, 0
	s_cmp_eq_u32 s3, 0
	v_lshlrev_b32_e32 v35, 16, v53
	v_lshlrev_b32_e32 v34, 16, v52
	v_and_b32_e32 v53, 0xffff0000, v53
	v_and_b32_e32 v52, 0xffff0000, v52
	v_lshlrev_b32_e32 v66, 16, v54
	v_lshlrev_b32_e32 v67, 16, v55
	v_lshlrev_b32_e32 v45, 16, v57
	v_lshlrev_b32_e32 v44, 16, v56
	v_and_b32_e32 v49, 0xffff0000, v57
	v_and_b32_e32 v48, 0xffff0000, v56
	v_and_b32_e32 v55, 0xffff0000, v55
	v_and_b32_e32 v54, 0xffff0000, v54
	v_pk_fma_f32 v[26:27], v[20:21], v[34:35], v[26:27]
	v_pk_fma_f32 v[30:31], v[22:23], v[52:53], v[30:31]
	v_lshlrev_b32_e32 v57, 16, v59
	v_lshlrev_b32_e32 v56, 16, v58
	v_and_b32_e32 v59, 0xffff0000, v59
	v_and_b32_e32 v58, 0xffff0000, v58
	v_pk_fma_f32 v[32:33], v[16:17], v[66:67], v[32:33]
	v_pk_fma_f32 v[36:37], v[18:19], v[54:55], v[36:37]
	v_pk_mul_f32 v[68:69], v[10:11], v[54:55]
	v_pk_fma_f32 v[70:71], v[14:15], v[52:53], v[50:51]
	v_pk_mul_f32 v[50:51], v[8:9], v[66:67]
	v_pk_mul_f32 v[26:27], v[26:27], v[44:45]
	v_pk_mul_f32 v[30:31], v[30:31], v[48:49]
	v_pk_mul_f32 v[32:33], v[32:33], v[56:57]
	v_pk_mul_f32 v[36:37], v[36:37], v[58:59]
	v_pk_fma_f32 v[56:57], v[0:1], v[42:43], v[50:51]
	v_pk_fma_f32 v[58:59], v[2:3], v[24:25], v[68:69]
	v_pk_mul_f32 v[24:25], v[26:27], v[26:27]
	v_pk_mul_f32 v[42:43], v[30:31], v[30:31]
	v_mov_b32_e32 v44, v37
	v_add_f32_e32 v24, v24, v42
	v_add_f32_e32 v24, v25, v24
	v_add_f32_e32 v24, v43, v24
	v_mov_b32_e32 v45, v33
	v_fmac_f32_e32 v24, v32, v32
; #define GAS __attribute__((address_space(1)))
; __device__ __forceinline__ unsigned pk2(float lo, float hi) { return f2bf(lo) | (f2bf(hi) << 16); }
; __device__ __forceinline__ void unpack8(const v4u w, float (&f)[8]) { f[0] = bflo(w.x); f[1] = bfhi(w.x); f[2] = bflo(w.y); f[3] = bfhi(w.y); f[4] = bflo(w.z); f[5] = bfhi(w.z); f[6] = bflo(w.w); f[7] = bfhi(w.w); }
; __device__ __forceinline__ float wave_sum(float v) {
; #pragma unroll
;     for (int o = 1; o < 64; o <<= 1) v += __shfl_xor(v, o);
;     return v;
; }
; __device__ __forceinline__ void attn_conv_unit(LAS unsigned char* lds, int unit, const bf16* Z, bf16* Y, float* RA,
;                                                const float* qg, const float* kg, const float* sinks, const float* convw) {
;     ...
;             unpack8(__builtin_nontemporal_load((const GAS v4u*)(Z + tok * ZLD + O_B + c0)), fb); unpack8(__builtin_nontemporal_load((const GAS v4u*)(Z + tok * ZLD + O_U + c0)), fu);
;             float ov[8]; float ss = 0.f;
; #pragma unroll
;             for (int e = 0; e < 8; ++e) { const float u0 = fu[e]; const float cv = w0[e] * u2[e] + w1[e] * u1[e] + w2[e] * u0; ov[e] = fb[e] * cv; ss += ov[e] * ov[e]; u2[e] = u1[e]; u1[e] = u0; }
;             const float r = 1.0f / sqrtf(wave_sum(ss) * (1.0f / CW) + EPS);
;             v4u o; o.x = pk2(ov[0] * r, ov[1] * r); o.y = pk2(ov[2] * r, ov[3] * r); o.z = pk2(ov[4] * r, ov[5] * r); o.w = pk2(ov[6] * r, ov[7] * r);
;             *(GAS v4u*)(Y + tok * D + AW + c0) = o;
	v_pk_mul_f32 v[44:45], v[44:45], v[44:45]
	v_fmac_f32_e32 v24, v36, v36
	v_add_f32_e32 v24, v45, v24
	v_add_f32_e32 v24, v44, v24
	s_nop 1
	v_add_f32_dpp v24, v24, v24 quad_perm:[1,0,3,2] row_mask:0xf bank_mask:0xf
	v_pk_fma_f32 v[60:61], v[12:13], v[34:35], v[60:61]
	v_pk_mul_f32 v[34:35], v[4:5], v[34:35]
	v_pk_mul_f32 v[52:53], v[6:7], v[52:53]
	v_add_f32_dpp v24, v24, v24 quad_perm:[2,3,0,1] row_mask:0xf bank_mask:0xf
	s_nop 1
	v_add_f32_dpp v24, v24, v24 row_half_mirror row_mask:0xf bank_mask:0xf
	s_nop 1
	v_add_f32_dpp v24, v24, v24 row_mirror row_mask:0xf bank_mask:0xf
	v_mov_b32_e32 v25, v24
	v_mov_b32_e32 v255, v24
	s_nop 1
	v_permlane16_swap_b32_e32 v25, v255
	v_add_f32_e32 v24, v25, v255
	v_mov_b32_e32 v25, v24
	v_mov_b32_e32 v255, v24
	s_nop 1
	v_permlane32_swap_b32_e32 v25, v255
	v_add_f32_e32 v24, v25, v255
	v_fmamk_f32 v24, v24, 0x3b000000, v169
	v_mul_f32_e32 v25, 0x4f800000, v24
	v_cmp_gt_f32_e32 vcc, s97, v24
	s_nop 1
	v_cndmask_b32_e32 v24, v24, v25, vcc
	v_sqrt_f32_e32 v25, v24
	s_nop 0
	v_add_u32_e32 v42, -1, v25
	v_add_u32_e32 v43, 1, v25
	v_fma_f32 v44, -v42, v25, v24
	v_fma_f32 v45, -v43, v25, v24
	v_cmp_ge_f32_e64 s[48:49], 0, v44
	s_nop 1
	v_cndmask_b32_e64 v25, v25, v42, s[48:49]
	v_cmp_lt_f32_e64 s[48:49], 0, v45
	s_nop 1
	v_cndmask_b32_e64 v25, v25, v43, s[48:49]
	v_mul_f32_e32 v42, 0x37800000, v25
	v_cndmask_b32_e32 v25, v25, v42, vcc
	v_cmp_class_f32_e32 vcc, v24, v170
	s_nop 1
	v_cndmask_b32_e32 v24, v25, v24, vcc
	v_div_scale_f32 v25, s[48:49], v24, v24, 1.0
	v_rcp_f32_e32 v43, v25
	v_div_scale_f32 v42, vcc, 1.0, v24, 1.0
	v_fma_f32 v44, -v25, v43, 1.0
	v_fmac_f32_e32 v43, v44, v43
	v_mul_f32_e32 v44, v42, v43
	v_fma_f32 v45, -v25, v44, v42
	v_fmac_f32_e32 v44, v45, v43
	v_fma_f32 v25, -v25, v44, v42
	v_div_fmas_f32 v25, v25, v43, v44
	v_div_fixup_f32 v24, v25, v24, 1.0
	v_pk_mul_f32 v[26:27], v[26:27], v[24:25] op_sel_hi:[1,0]
	v_pk_mul_f32 v[32:33], v[32:33], v[24:25] op_sel_hi:[1,0]
	v_pk_mul_f32 v[30:31], v[30:31], v[24:25] op_sel_hi:[1,0]
	v_pk_mul_f32 v[24:25], v[36:37], v[24:25] op_sel_hi:[1,0]
	v_bfe_u32 v44, v26, 16, 1
	v_bfe_u32 v45, v27, 16, 1
	v_bfe_u32 v48, v32, 16, 1
	v_bfe_u32 v49, v33, 16, 1
	v_bfe_u32 v36, v25, 16, 1
	v_bfe_u32 v37, v24, 16, 1
	v_bfe_u32 v42, v31, 16, 1
	v_bfe_u32 v43, v30, 16, 1
	v_add3_u32 v33, v33, v49, s98
	v_add3_u32 v32, v32, v48, s98
	v_add3_u32 v27, v27, v45, s98
	v_add3_u32 v26, v26, v44, s98
	v_add3_u32 v30, v30, v43, s98
	v_add3_u32 v31, v31, v42, s98
	v_add3_u32 v24, v24, v37, s98
	v_add3_u32 v25, v25, v36, s98
	v_lshrrev_b32_e32 v36, 16, v26
	v_lshrrev_b32_e32 v37, 16, v27
	v_lshrrev_b32_e32 v26, 16, v32
	v_lshrrev_b32_e32 v27, 16, v33
	v_and_or_b32 v27, v25, s96, v27
	v_and_or_b32 v26, v24, s96, v26
	v_and_or_b32 v25, v31, s96, v37
	v_and_or_b32 v24, v30, s96, v36
	global_store_dwordx4 v[38:39], v[24:27], off
	s_waitcnt vmcnt(11)
	v_lshl_add_u64 v[252:253], v[40:41], 0, s[100:101]
	v_mov_b32_e32 v24, v190
	v_mov_b32_e32 v25, v191
	v_mov_b32_e32 v26, v192
	v_mov_b32_e32 v27, v193
	global_load_dwordx4 v[190:193], v[252:253], off offset:2048 nt
	s_nop 0
	s_waitcnt vmcnt(11)
	v_lshl_add_u64 v[252:253], v[40:41], 0, s[100:101]
	v_mov_b32_e32 v30, v194
	v_mov_b32_e32 v31, v195
	v_mov_b32_e32 v32, v196
	v_mov_b32_e32 v33, v197
	global_load_dwordx4 v[194:197], v[252:253], off offset:1024 nt
	v_lshlrev_b32_e32 v45, 16, v25
	v_lshlrev_b32_e32 v44, 16, v24
	v_and_b32_e32 v49, 0xffff0000, v25
	v_and_b32_e32 v48, 0xffff0000, v24
	v_lshlrev_b32_e32 v42, 16, v26
	v_lshlrev_b32_e32 v43, 16, v27
	v_lshlrev_b32_e32 v37, 16, v31
	v_lshlrev_b32_e32 v36, 16, v30
	v_and_b32_e32 v31, 0xffff0000, v31
	v_and_b32_e32 v30, 0xffff0000, v30
	v_and_b32_e32 v51, 0xffff0000, v27
	v_and_b32_e32 v50, 0xffff0000, v26
	v_pk_fma_f32 v[26:27], v[20:21], v[44:45], v[60:61]
	v_pk_fma_f32 v[38:39], v[22:23], v[48:49], v[70:71]
	v_lshlrev_b32_e32 v25, 16, v33
	v_lshlrev_b32_e32 v24, 16, v32
	v_and_b32_e32 v33, 0xffff0000, v33
	v_and_b32_e32 v32, 0xffff0000, v32
	v_pk_fma_f32 v[40:41], v[16:17], v[42:43], v[56:57]
	v_pk_fma_f32 v[56:57], v[18:19], v[50:51], v[58:59]
	v_pk_fma_f32 v[60:61], v[12:13], v[44:45], v[34:35]
	v_pk_mul_f32 v[34:35], v[8:9], v[42:43]
	v_pk_mul_f32 v[26:27], v[26:27], v[36:37]
	v_pk_mul_f32 v[30:31], v[38:39], v[30:31]
	v_pk_mul_f32 v[32:33], v[56:57], v[32:33]
	v_pk_fma_f32 v[56:57], v[0:1], v[66:67], v[34:35]
	v_pk_mul_f32 v[34:35], v[26:27], v[26:27]
	v_pk_mul_f32 v[36:37], v[30:31], v[30:31]
	v_pk_mul_f32 v[24:25], v[40:41], v[24:25]
	v_add_f32_e32 v34, v34, v36
	v_add_f32_e32 v34, v35, v34
	v_add_f32_e32 v34, v37, v34
	v_mov_b32_e32 v38, v33
	v_mov_b32_e32 v39, v25
	v_fmac_f32_e32 v34, v24, v24
	v_pk_mul_f32 v[38:39], v[38:39], v[38:39]
	v_fmac_f32_e32 v34, v32, v32
	v_add_f32_e32 v34, v39, v34
	v_add_f32_e32 v34, v38, v34
	s_nop 1
	v_add_f32_dpp v34, v34, v34 quad_perm:[1,0,3,2] row_mask:0xf bank_mask:0xf
	v_pk_mul_f32 v[58:59], v[10:11], v[50:51]
	v_pk_fma_f32 v[68:69], v[14:15], v[48:49], v[52:53]
	v_pk_fma_f32 v[58:59], v[2:3], v[54:55], v[58:59]
	v_pk_mul_f32 v[48:49], v[6:7], v[48:49]
	v_add_f32_dpp v34, v34, v34 quad_perm:[2,3,0,1] row_mask:0xf bank_mask:0xf
	v_pk_mul_f32 v[44:45], v[4:5], v[44:45]
	s_nop 0
	v_add_f32_dpp v34, v34, v34 row_half_mirror row_mask:0xf bank_mask:0xf
	s_nop 1
	v_add_f32_dpp v34, v34, v34 row_mirror row_mask:0xf bank_mask:0xf
	v_mov_b32_e32 v35, v34
	v_mov_b32_e32 v255, v34
	s_nop 1
	v_permlane16_swap_b32_e32 v35, v255
	v_add_f32_e32 v34, v35, v255
	v_mov_b32_e32 v35, v34
	v_mov_b32_e32 v255, v34
	s_nop 1
	v_permlane32_swap_b32_e32 v35, v255
	v_add_f32_e32 v34, v35, v255
	v_fmamk_f32 v34, v34, 0x3b000000, v169
	v_mul_f32_e32 v35, 0x4f800000, v34
; #define GAS __attribute__((address_space(1)))
; __device__ __forceinline__ unsigned pk2(float lo, float hi) { return f2bf(lo) | (f2bf(hi) << 16); }
; __device__ __forceinline__ void unpack8(const v4u w, float (&f)[8]) { f[0] = bflo(w.x); f[1] = bfhi(w.x); f[2] = bflo(w.y); f[3] = bfhi(w.y); f[4] = bflo(w.z); f[5] = bfhi(w.z); f[6] = bflo(w.w); f[7] = bfhi(w.w); }
; __device__ __forceinline__ float wave_sum(float v) {
; #pragma unroll
;     for (int o = 1; o < 64; o <<= 1) v += __shfl_xor(v, o);
;     return v;
; }
; __device__ __forceinline__ void attn_conv_unit(LAS unsigned char* lds, int unit, const bf16* Z, bf16* Y, float* RA,
;                                                const float* qg, const float* kg, const float* sinks, const float* convw) {
;     ...
;             unpack8(__builtin_nontemporal_load((const GAS v4u*)(Z + tok * ZLD + O_B + c0)), fb); unpack8(__builtin_nontemporal_load((const GAS v4u*)(Z + tok * ZLD + O_U + c0)), fu);
;             float ov[8]; float ss = 0.f;
; #pragma unroll
;             for (int e = 0; e < 8; ++e) { const float u0 = fu[e]; const float cv = w0[e] * u2[e] + w1[e] * u1[e] + w2[e] * u0; ov[e] = fb[e] * cv; ss += ov[e] * ov[e]; u2[e] = u1[e]; u1[e] = u0; }
;             const float r = 1.0f / sqrtf(wave_sum(ss) * (1.0f / CW) + EPS);
;             v4u o; o.x = pk2(ov[0] * r, ov[1] * r); o.y = pk2(ov[2] * r, ov[3] * r); o.z = pk2(ov[4] * r, ov[5] * r); o.w = pk2(ov[6] * r, ov[7] * r);
;             *(GAS v4u*)(Y + tok * D + AW + c0) = o;
	v_cmp_gt_f32_e32 vcc, s97, v34
	s_nop 1
	v_cndmask_b32_e32 v34, v34, v35, vcc
	v_sqrt_f32_e32 v35, v34
	s_nop 0
	v_add_u32_e32 v36, -1, v35
	v_add_u32_e32 v37, 1, v35
	v_fma_f32 v38, -v36, v35, v34
	v_fma_f32 v39, -v37, v35, v34
	v_cmp_ge_f32_e64 s[48:49], 0, v38
	s_nop 1
	v_cndmask_b32_e64 v35, v35, v36, s[48:49]
	v_cmp_lt_f32_e64 s[48:49], 0, v39
	s_nop 1
	v_cndmask_b32_e64 v35, v35, v37, s[48:49]
	v_mul_f32_e32 v36, 0x37800000, v35
	v_cndmask_b32_e32 v35, v35, v36, vcc
	v_cmp_class_f32_e32 vcc, v34, v170
	s_nop 1
	v_cndmask_b32_e32 v34, v35, v34, vcc
	v_div_scale_f32 v35, s[48:49], v34, v34, 1.0
	v_rcp_f32_e32 v37, v35
	v_div_scale_f32 v36, vcc, 1.0, v34, 1.0
	v_fma_f32 v38, -v35, v37, 1.0
	v_fmac_f32_e32 v37, v38, v37
	v_mul_f32_e32 v38, v36, v37
	v_fma_f32 v39, -v35, v38, v36
	v_fmac_f32_e32 v38, v39, v37
	v_fma_f32 v35, -v35, v38, v36
	v_div_fmas_f32 v35, v35, v37, v38
	v_div_fixup_f32 v34, v35, v34, 1.0
	v_pk_mul_f32 v[26:27], v[26:27], v[34:35] op_sel_hi:[1,0]
	v_pk_mul_f32 v[24:25], v[24:25], v[34:35] op_sel_hi:[1,0]
	v_pk_mul_f32 v[30:31], v[30:31], v[34:35] op_sel_hi:[1,0]
	v_pk_mul_f32 v[32:33], v[32:33], v[34:35] op_sel_hi:[1,0]
	v_bfe_u32 v38, v26, 16, 1
	v_bfe_u32 v39, v27, 16, 1
	v_bfe_u32 v40, v24, 16, 1
	v_bfe_u32 v41, v25, 16, 1
	v_bfe_u32 v34, v33, 16, 1
	v_bfe_u32 v35, v32, 16, 1
	v_bfe_u32 v36, v31, 16, 1
	v_bfe_u32 v37, v30, 16, 1
	v_add3_u32 v25, v25, v41, s98
	v_add3_u32 v24, v24, v40, s98
	v_add3_u32 v27, v27, v39, s98
	v_add3_u32 v26, v26, v38, s98
	v_add3_u32 v30, v30, v37, s98
	v_add3_u32 v31, v31, v36, s98
	v_add3_u32 v32, v32, v35, s98
	v_add3_u32 v33, v33, v34, s98
	v_lshrrev_b32_e32 v34, 16, v26
	v_lshrrev_b32_e32 v35, 16, v27
	v_lshrrev_b32_e32 v24, 16, v24
	v_lshrrev_b32_e32 v25, 16, v25
	v_and_or_b32 v27, v33, s96, v25
	v_and_or_b32 v26, v32, s96, v24
	v_and_or_b32 v25, v31, s96, v35
	v_and_or_b32 v24, v30, s96, v34
	global_store_dwordx4 v[62:63], v[24:27], off offset:3072
	s_waitcnt vmcnt(11)
	v_lshl_add_u64 v[252:253], v[64:65], 0, s[100:101]
	v_mov_b32_e32 v24, v198
	v_mov_b32_e32 v25, v199
	v_mov_b32_e32 v26, v200
	v_mov_b32_e32 v27, v201
	global_load_dwordx4 v[198:201], v[252:253], off offset:1536 nt
	s_nop 0
	s_waitcnt vmcnt(11)
	v_lshl_add_u64 v[252:253], v[64:65], 0, s[100:101]
	v_mov_b32_e32 v52, v202
	v_mov_b32_e32 v53, v203
	v_mov_b32_e32 v54, v204
	v_mov_b32_e32 v55, v205
	global_load_dwordx4 v[202:205], v[252:253], off offset:512 nt
	v_lshlrev_b32_e32 v38, 16, v24
	v_lshlrev_b32_e32 v35, 16, v25
	v_and_b32_e32 v41, 0xffff0000, v25
	v_and_b32_e32 v40, 0xffff0000, v24
	v_mov_b32_e32 v34, v38
	v_lshlrev_b32_e32 v39, 16, v26
	v_lshlrev_b32_e32 v33, 16, v27
	v_lshlrev_b32_e32 v31, 16, v53
	v_lshlrev_b32_e32 v30, 16, v52
	v_and_b32_e32 v53, 0xffff0000, v53
	v_and_b32_e32 v52, 0xffff0000, v52
	v_and_b32_e32 v37, 0xffff0000, v27
	v_and_b32_e32 v36, 0xffff0000, v26
	v_pk_fma_f32 v[26:27], v[22:23], v[40:41], v[68:69]
	v_pk_fma_f32 v[60:61], v[20:21], v[34:35], v[60:61]
	v_lshlrev_b32_e32 v25, 16, v55
	v_lshlrev_b32_e32 v24, 16, v54
	v_and_b32_e32 v55, 0xffff0000, v55
	v_and_b32_e32 v54, 0xffff0000, v54
	v_mov_b32_e32 v32, v39
	v_pk_fma_f32 v[58:59], v[18:19], v[36:37], v[58:59]
	v_pk_mul_f32 v[26:27], v[26:27], v[52:53]
	v_pk_mul_f32 v[30:31], v[60:61], v[30:31]
	v_pk_fma_f32 v[52:53], v[16:17], v[32:33], v[56:57]
	v_pk_mul_f32 v[54:55], v[58:59], v[54:55]
	v_pk_mul_f32 v[56:57], v[26:27], v[26:27]
	v_pk_mul_f32 v[58:59], v[30:31], v[30:31]
	v_pk_mul_f32 v[24:25], v[52:53], v[24:25]
	v_add_f32_e32 v56, v58, v56
	v_add_f32_e32 v56, v59, v56
	v_add_f32_e32 v56, v57, v56
	v_mov_b32_e32 v52, v55
	v_mov_b32_e32 v53, v25
	v_fmac_f32_e32 v56, v24, v24
	v_pk_mul_f32 v[52:53], v[52:53], v[52:53]
	v_fmac_f32_e32 v56, v54, v54
	v_add_f32_e32 v53, v53, v56
	v_add_f32_e32 v52, v52, v53
	s_nop 1
	v_add_f32_dpp v52, v52, v52 quad_perm:[1,0,3,2] row_mask:0xf bank_mask:0xf
	s_nop 1
	v_add_f32_dpp v52, v52, v52 quad_perm:[2,3,0,1] row_mask:0xf bank_mask:0xf
	s_nop 1
	v_add_f32_dpp v52, v52, v52 row_half_mirror row_mask:0xf bank_mask:0xf
	s_nop 1
	v_add_f32_dpp v52, v52, v52 row_mirror row_mask:0xf bank_mask:0xf
	v_mov_b32_e32 v53, v52
	v_mov_b32_e32 v255, v52
	s_nop 1
	v_permlane16_swap_b32_e32 v53, v255
	v_add_f32_e32 v52, v53, v255
	v_mov_b32_e32 v53, v52
	v_mov_b32_e32 v255, v52
	s_nop 1
	v_permlane32_swap_b32_e32 v53, v255
	v_add_f32_e32 v52, v53, v255
	v_fmamk_f32 v52, v52, 0x3b000000, v169
	v_mul_f32_e32 v53, 0x4f800000, v52
	v_cmp_gt_f32_e32 vcc, s97, v52
	s_nop 1
	v_cndmask_b32_e32 v52, v52, v53, vcc
	v_sqrt_f32_e32 v53, v52
	s_nop 0
	v_add_u32_e32 v56, -1, v53
	v_add_u32_e32 v57, 1, v53
	v_fma_f32 v58, -v56, v53, v52
	v_fma_f32 v59, -v57, v53, v52
	v_cmp_ge_f32_e64 s[48:49], 0, v58
	s_nop 1
	v_cndmask_b32_e64 v53, v53, v56, s[48:49]
	v_cmp_lt_f32_e64 s[48:49], 0, v59
	s_nop 1
	v_cndmask_b32_e64 v53, v53, v57, s[48:49]
	v_mul_f32_e32 v56, 0x37800000, v53
	v_cndmask_b32_e32 v53, v53, v56, vcc
	v_cmp_class_f32_e32 vcc, v52, v170
	s_nop 1
	v_cndmask_b32_e32 v52, v53, v52, vcc
	v_div_scale_f32 v53, s[48:49], v52, v52, 1.0
	v_rcp_f32_e32 v57, v53
	v_div_scale_f32 v56, vcc, 1.0, v52, 1.0
	v_fma_f32 v58, -v53, v57, 1.0
	v_fmac_f32_e32 v57, v58, v57
	v_mul_f32_e32 v58, v56, v57
	v_fma_f32 v59, -v53, v58, v56
	v_fmac_f32_e32 v58, v59, v57
	v_fma_f32 v53, -v53, v58, v56
	v_div_fmas_f32 v53, v53, v57, v58
	v_div_fixup_f32 v52, v53, v52, 1.0
	v_pk_mul_f32 v[30:31], v[30:31], v[52:53] op_sel_hi:[1,0]
	v_pk_mul_f32 v[24:25], v[24:25], v[52:53] op_sel_hi:[1,0]
	v_pk_mul_f32 v[26:27], v[26:27], v[52:53] op_sel_hi:[1,0]
	v_pk_mul_f32 v[52:53], v[54:55], v[52:53] op_sel_hi:[1,0]
	v_bfe_u32 v58, v30, 16, 1
	v_bfe_u32 v59, v31, 16, 1
	v_bfe_u32 v60, v24, 16, 1
	v_bfe_u32 v61, v25, 16, 1
	v_bfe_u32 v54, v53, 16, 1
	v_bfe_u32 v55, v52, 16, 1
	v_bfe_u32 v56, v27, 16, 1
	v_bfe_u32 v57, v26, 16, 1
	v_add3_u32 v25, v25, v61, s98
	v_add3_u32 v24, v24, v60, s98
	v_add3_u32 v31, v31, v59, s98
	v_add3_u32 v30, v30, v58, s98
	v_add3_u32 v57, v26, v57, s98
	v_add3_u32 v56, v27, v56, s98
	v_add3_u32 v26, v52, v55, s98
	v_add3_u32 v27, v53, v54, s98
	v_lshrrev_b32_e32 v30, 16, v30
	v_lshrrev_b32_e32 v31, 16, v31
	v_lshrrev_b32_e32 v24, 16, v24
	v_lshrrev_b32_e32 v25, 16, v25
	v_and_or_b32 v27, v27, s96, v25
	v_and_or_b32 v26, v26, s96, v24
	v_and_or_b32 v25, v56, s96, v31
	v_and_or_b32 v24, v57, s96, v30
	global_store_dwordx4 v[46:47], v[24:27], off offset:1024
	s_waitcnt vmcnt(11)
; #define GAS __attribute__((address_space(1)))
; #define LAS __attribute__((address_space(3)))
; __device__ __forceinline__ unsigned pk2(float lo, float hi) { return f2bf(lo) | (f2bf(hi) << 16); }
; __device__ __forceinline__ void unpack8(const v4u w, float (&f)[8]) { f[0] = bflo(w.x); f[1] = bfhi(w.x); f[2] = bflo(w.y); f[3] = bfhi(w.y); f[4] = bflo(w.z); f[5] = bfhi(w.z); f[6] = bflo(w.w); f[7] = bfhi(w.w); }
; __device__ __forceinline__ void attn_conv_unit(LAS unsigned char* lds, int unit, const bf16* Z, bf16* Y, float* RA,
;                                                const float* qg, const float* kg, const float* sinks, const float* convw) {
;     ...
;             unpack8(__builtin_nontemporal_load((const GAS v4u*)(Z + tok * ZLD + O_B + c0)), fb); unpack8(__builtin_nontemporal_load((const GAS v4u*)(Z + tok * ZLD + O_U + c0)), fu);
;             float ov[8]; float ss = 0.f;
; #pragma unroll
;             for (int e = 0; e < 8; ++e) { const float u0 = fu[e]; const float cv = w0[e] * u2[e] + w1[e] * u1[e] + w2[e] * u0; ov[e] = fb[e] * cv; ss += ov[e] * ov[e]; u2[e] = u1[e]; u1[e] = u0; }
;             const float r = 1.0f / sqrtf(wave_sum(ss) * (1.0f / CW) + EPS);
;             v4u o; o.x = pk2(ov[0] * r, ov[1] * r); o.y = pk2(ov[2] * r, ov[3] * r); o.z = pk2(ov[4] * r, ov[5] * r); o.w = pk2(ov[6] * r, ov[7] * r);
;             *(GAS v4u*)(Y + tok * D + AW + c0) = o;
;         }
;     }
;     __syncthreads();
;     {
;         const int h = wave, kvh = h >> 2, r32 = lane & 31, hi = lane >> 5;
;         const float sink2 = sinks[h] * LOG2E;
;         const LAS unsigned char* ksb = lds + LDS_KS + (kvh * 256 + r32) * KS_STRIDE + hi * 16;
;         const LAS unsigned char* vtb = lds + LDS_VT + (kvh * 64 + r32) * VT_STRIDE + hi * 8;
;         LAS float* SS = (LAS float*)(lds + LDS_SS);
;         v4u qw[4];
; #pragma unroll
;         for (int ks = 0; ks < 4; ++ks) qw[ks] = __builtin_nontemporal_load((const GAS v4u*)(Z + (tok0 + r32) * ZLD + h * 64 + ks * 16 + hi * 8));
	v_lshl_add_u64 v[252:253], v[28:29], 0, s[100:101]
	v_mov_b32_e32 v24, v206
	v_mov_b32_e32 v25, v207
	v_mov_b32_e32 v26, v208
	v_mov_b32_e32 v27, v209
	global_load_dwordx4 v[206:209], v[252:253], off offset:1024 nt
	s_nop 0
	s_waitcnt vmcnt(11)
	v_lshl_add_u64 v[252:253], v[28:29], 0, s[100:101]
	v_mov_b32_e32 v28, v210
	v_mov_b32_e32 v29, v211
	v_mov_b32_e32 v30, v212
	v_mov_b32_e32 v31, v213
	global_load_dwordx4 v[210:213], v[252:253], off nt
	v_pk_mul_f32 v[52:53], v[10:11], v[36:37]
	v_pk_fma_f32 v[54:55], v[14:15], v[40:41], v[48:49]
	v_pk_fma_f32 v[56:57], v[12:13], v[34:35], v[44:45]
	v_pk_mul_f32 v[44:45], v[8:9], v[32:33]
	v_pk_fma_f32 v[50:51], v[2:3], v[50:51], v[52:53]
	v_pk_fma_f32 v[52:53], v[0:1], v[42:43], v[44:45]
	v_lshlrev_b32_e32 v48, 16, v24
	v_lshlrev_b32_e32 v45, 16, v25
	v_lshlrev_b32_e32 v59, 16, v29
	v_lshlrev_b32_e32 v58, 16, v28
	v_and_b32_e32 v61, 0xffff0000, v29
	v_and_b32_e32 v60, 0xffff0000, v28
	v_and_b32_e32 v29, 0xffff0000, v25
	v_and_b32_e32 v28, 0xffff0000, v24
	v_and_b32_e32 v25, 0xffff0000, v27
	v_and_b32_e32 v24, 0xffff0000, v26
	v_mov_b32_e32 v44, v48
	v_lshlrev_b32_e32 v49, 16, v26
	v_lshlrev_b32_e32 v43, 16, v27
	v_lshlrev_b32_e32 v63, 16, v31
	v_lshlrev_b32_e32 v62, 16, v30
	v_and_b32_e32 v31, 0xffff0000, v31
	v_and_b32_e32 v30, 0xffff0000, v30
	v_pk_fma_f32 v[26:27], v[22:23], v[28:29], v[54:55]
	v_pk_fma_f32 v[50:51], v[18:19], v[24:25], v[50:51]
	v_pk_fma_f32 v[54:55], v[20:21], v[44:45], v[56:57]
	v_pk_mul_f32 v[26:27], v[26:27], v[60:61]
	v_pk_mul_f32 v[30:31], v[50:51], v[30:31]
	v_pk_mul_f32 v[50:51], v[54:55], v[58:59]
	v_pk_mul_f32 v[54:55], v[26:27], v[26:27]
	v_pk_mul_f32 v[58:59], v[50:51], v[50:51]
	v_mov_b32_e32 v42, v49
	v_add_f32_e32 v32, v58, v54
	v_pk_fma_f32 v[52:53], v[16:17], v[42:43], v[52:53]
	v_add_f32_e32 v32, v59, v32
	v_pk_mul_f32 v[52:53], v[52:53], v[62:63]
	v_add_f32_e32 v32, v55, v32
	v_mov_b32_e32 v56, v31
	v_mov_b32_e32 v57, v53
	v_fmac_f32_e32 v32, v52, v52
	v_pk_mul_f32 v[56:57], v[56:57], v[56:57]
	v_fmac_f32_e32 v32, v30, v30
	v_add_f32_e32 v32, v57, v32
	v_add_f32_e32 v32, v56, v32
	s_nop 1
	v_add_f32_dpp v32, v32, v32 quad_perm:[1,0,3,2] row_mask:0xf bank_mask:0xf
	s_nop 1
	v_add_f32_dpp v32, v32, v32 quad_perm:[2,3,0,1] row_mask:0xf bank_mask:0xf
	s_nop 1
	v_add_f32_dpp v32, v32, v32 row_half_mirror row_mask:0xf bank_mask:0xf
	s_nop 1
	v_add_f32_dpp v32, v32, v32 row_mirror row_mask:0xf bank_mask:0xf
	v_mov_b32_e32 v34, v32
	v_mov_b32_e32 v255, v32
	s_nop 1
	v_permlane16_swap_b32_e32 v34, v255
	v_add_f32_e32 v32, v34, v255
	v_mov_b32_e32 v34, v32
	v_mov_b32_e32 v255, v32
	s_nop 1
	v_permlane32_swap_b32_e32 v34, v255
	v_add_f32_e32 v32, v34, v255
	v_fmamk_f32 v32, v32, 0x3b000000, v169
	v_mul_f32_e32 v34, 0x4f800000, v32
	v_cmp_gt_f32_e32 vcc, s97, v32
	s_nop 1
	v_cndmask_b32_e32 v32, v32, v34, vcc
	v_sqrt_f32_e32 v34, v32
	s_nop 0
	v_add_u32_e32 v42, -1, v34
	v_add_u32_e32 v44, 1, v34
	v_fma_f32 v54, -v42, v34, v32
	v_fma_f32 v55, -v44, v34, v32
	v_cmp_ge_f32_e64 s[48:49], 0, v54
	s_nop 1
	v_cndmask_b32_e64 v34, v34, v42, s[48:49]
	v_cmp_lt_f32_e64 s[48:49], 0, v55
	s_nop 1
	v_cndmask_b32_e64 v34, v34, v44, s[48:49]
	v_mul_f32_e32 v42, 0x37800000, v34
	v_cndmask_b32_e32 v34, v34, v42, vcc
	v_cmp_class_f32_e32 vcc, v32, v170
	s_nop 1
	v_cndmask_b32_e32 v32, v34, v32, vcc
	v_div_scale_f32 v34, s[48:49], v32, v32, 1.0
	v_rcp_f32_e32 v44, v34
	v_div_scale_f32 v42, vcc, 1.0, v32, 1.0
	v_fma_f32 v54, -v34, v44, 1.0
	v_fmac_f32_e32 v44, v54, v44
	v_mul_f32_e32 v54, v42, v44
	v_fma_f32 v55, -v34, v54, v42
	v_fmac_f32_e32 v54, v55, v44
	v_fma_f32 v34, -v34, v54, v42
	v_div_fmas_f32 v34, v34, v44, v54
	v_div_fixup_f32 v32, v34, v32, 1.0
	v_pk_mul_f32 v[50:51], v[50:51], v[32:33] op_sel_hi:[1,0]
	v_pk_mul_f32 v[26:27], v[26:27], v[32:33] op_sel_hi:[1,0]
	v_pk_mul_f32 v[52:53], v[52:53], v[32:33] op_sel_hi:[1,0]
	v_pk_mul_f32 v[30:31], v[30:31], v[32:33] op_sel_hi:[1,0]
	v_bfe_u32 v42, v27, 16, 1
	v_bfe_u32 v32, v31, 16, 1
	v_bfe_u32 v34, v30, 16, 1
	v_bfe_u32 v44, v26, 16, 1
	v_bfe_u32 v54, v50, 16, 1
	v_bfe_u32 v55, v51, 16, 1
	v_bfe_u32 v56, v52, 16, 1
	v_bfe_u32 v57, v53, 16, 1
	v_add3_u32 v26, v26, v44, s98
	v_add3_u32 v27, v27, v42, s98
	v_add3_u32 v30, v30, v34, s98
	v_add3_u32 v31, v31, v32, s98
	v_add3_u32 v32, v53, v57, s98
	v_add3_u32 v34, v52, v56, s98
	v_add3_u32 v42, v51, v55, s98
	v_add3_u32 v44, v50, v54, s98
	v_lshrrev_b32_e32 v44, 16, v44
	v_lshrrev_b32_e32 v42, 16, v42
	v_lshrrev_b32_e32 v34, 16, v34
	v_lshrrev_b32_e32 v32, 16, v32
	v_and_or_b32 v53, v31, s96, v32
	v_and_or_b32 v52, v30, s96, v34
	v_and_or_b32 v51, v27, s96, v42
	v_and_or_b32 v50, v26, s96, v44
	global_store_dwordx4 v[46:47], v[50:53], off offset:3072
	s_cbranch_scc0 .LBB0_436
	s_lshl_b32 s60, s78, 2
	v_mov_b32_e32 v0, s60
	s_waitcnt lgkmcnt(0)
	s_barrier
	global_load_dword v6, v0, s[58:59]
	v_or_b32_e32 v2, s54, v128
	v_mov_b64_e32 v[0:1], s[66:67]
	v_mad_u64_u32 v[0:1], s[48:49], v2, s92, v[0:1]
	s_and_b32 s48, s76, 0xffffffc0
	s_ashr_i32 s49, s48, 31
	v_add_u32_e32 v1, s46, v1
	s_lshl_b64 s[48:49], s[48:49], 1
	v_lshl_add_u64 v[0:1], v[0:1], 0, s[48:49]
	v_mov_b32_e32 v157, v131
	v_lshl_add_u64 v[0:1], v[0:1], 0, v[156:157]
	global_load_dwordx4 v[80:83], v[0:1], off nt
	global_load_dwordx4 v[84:87], v[0:1], off offset:32 nt
	global_load_dwordx4 v[88:91], v[0:1], off offset:64 nt
	global_load_dwordx4 v[92:95], v[0:1], off offset:96 nt
	s_cmp_eq_u32 s77, 0
	v_add_u32_e32 v143, s60, v167
	s_cselect_b64 s[60:61], -1, 0
	s_add_u32 s46, s47, s56
	s_addc_u32 s47, s57, 0
	v_mov_b64_e32 v[0:1], s[48:49]
	v_lshl_add_u64 v[2:3], s[46:47], 0, v[128:129]
	s_lshr_b32 s56, s76, 8
	v_mad_u64_u32 v[0:1], s[46:47], v2, s92, v[0:1]
	v_lshlrev_b64 v[4:5], 11, v[2:3]
	s_mul_i32 s57, s56, 0x8200
	v_mad_i32_i24 v1, v3, s92, v1
	v_lshl_add_u64 v[2:3], v[4:5], 0, s[48:49]
	s_mul_i32 s56, s56, 0x9000
	s_mov_b32 s3, 0
	v_add_u32_e32 v145, s57, v166
	v_lshl_add_u64 v[158:159], v[138:139], 0, v[0:1]
	v_lshl_add_u64 v[160:161], v[140:141], 0, v[2:3]
	v_add_u32_e32 v149, s56, v168
	s_mov_b32 s46, 0
	s_waitcnt vmcnt(4)
	v_mul_f32_e32 v147, 0x3fb8aa3b, v6
	s_branch .LBB0_439

; __global__ void __launch_bounds__(NWAVES * 64, 2) hymba_fwd(Args args) {
	.amdhsa_kernel _Z9hymba_fwd4Args
		.amdhsa_group_segment_fixed_size 0
		.amdhsa_private_segment_fixed_size 0
		.amdhsa_kernarg_size 384
		.amdhsa_user_sgpr_count 2
		.amdhsa_user_sgpr_dispatch_ptr 0
		.amdhsa_user_sgpr_queue_ptr 0
		.amdhsa_user_sgpr_kernarg_segment_ptr 1
		.amdhsa_user_sgpr_dispatch_id 0
		.amdhsa_user_sgpr_kernarg_preload_length 0
		.amdhsa_user_sgpr_kernarg_preload_offset 0
		.amdhsa_user_sgpr_private_segment_size 0
		.amdhsa_uses_dynamic_stack 0
		.amdhsa_enable_private_segment 0
		.amdhsa_system_sgpr_workgroup_id_x 1
		.amdhsa_system_sgpr_workgroup_id_y 0
		.amdhsa_system_sgpr_workgroup_id_z 0
		.amdhsa_system_sgpr_workgroup_info 0
		.amdhsa_system_vgpr_workitem_id 2
		.amdhsa_next_free_vgpr 256
		.amdhsa_next_free_sgpr 102
		.amdhsa_accum_offset 256
		.amdhsa_reserve_vcc 1
		.amdhsa_float_round_mode_32 0
		.amdhsa_float_round_mode_16_64 0
		.amdhsa_float_denorm_mode_32 3
		.amdhsa_float_denorm_mode_16_64 3
		.amdhsa_dx10_clamp 1
		.amdhsa_ieee_mode 1
		.amdhsa_fp16_overflow 0
		.amdhsa_tg_split 0
		.amdhsa_exception_fp_ieee_invalid_op 0
		.amdhsa_exception_fp_denorm_src 0
		.amdhsa_exception_fp_ieee_div_zero 0
		.amdhsa_exception_fp_ieee_overflow 0
		.amdhsa_exception_fp_ieee_underflow 0
		.amdhsa_exception_fp_ieee_inexact 0
		.amdhsa_exception_int_div_zero 0
	.end_amdhsa_kernel

; __global__ void __launch_bounds__(NWAVES * 64, 2) hymba_fwd(Args args) {
amdhsa.kernels:
  - .agpr_count:     0
    .args:
      - .offset:         0
        .size:           128
        .value_kind:     by_value
      - .offset:         128
        .size:           4
        .value_kind:     hidden_block_count_x
      - .offset:         132
        .size:           4
        .value_kind:     hidden_block_count_y
      - .offset:         136
        .size:           4
        .value_kind:     hidden_block_count_z
      - .offset:         140
        .size:           2
        .value_kind:     hidden_group_size_x
      - .offset:         142
        .size:           2
        .value_kind:     hidden_group_size_y
      - .offset:         144
        .size:           2
        .value_kind:     hidden_group_size_z
      - .offset:         146
        .size:           2
        .value_kind:     hidden_remainder_x
      - .offset:         148
        .size:           2
        .value_kind:     hidden_remainder_y
      - .offset:         150
        .size:           2
        .value_kind:     hidden_remainder_z
      - .offset:         168
        .size:           8
        .value_kind:     hidden_global_offset_x
      - .offset:         176
        .size:           8
        .value_kind:     hidden_global_offset_y
      - .offset:         184
        .size:           8
        .value_kind:     hidden_global_offset_z
      - .offset:         192
        .size:           2
        .value_kind:     hidden_grid_dims
      - .offset:         216
        .size:           8
        .value_kind:     hidden_multigrid_sync_arg
      - .offset:         248
        .size:           4
        .value_kind:     hidden_dynamic_lds_size
    .group_segment_fixed_size: 0
    .kernarg_segment_align: 8
    .kernarg_segment_size: 384
    .language:       OpenCL C
    .language_version:
      - 2
      - 0
    .max_flat_workgroup_size: 512
    .name:           _Z9hymba_fwd4Args
    .private_segment_fixed_size: 0
    .sgpr_count:     108
    .sgpr_spill_count: 36
    .symbol:         _Z9hymba_fwd4Args.kd
    .uniform_work_group_size: 1
    .uses_dynamic_stack: false
    .vgpr_count:     256
    .vgpr_spill_count: 0
    .wavefront_size: 64
